# out-proj GEMM: LDS-DMA staging + per-CU rotated K order (L2-channel de-camping), hand-written epilogue on the loop's canonical accumulators
# baseline (speedup 1.0000x reference)
; DI int tidx() { int t = threadIdx.x; asm volatile("" : "+v"(t)); return t; }
; template <int EPI>
; DI void gemm_phase(const P& p, int l, const u16* __restrict__ A, const u16* __restrict__ Bt, int mpx, char* lds) {
;   const int tid = tidx();
;   int t = 0;
;   int m0, n0;
;   if (!tile_coords<EPI>(t, mpx, m0, n0)) return;
;   const unsigned voffb = (unsigned)(((tid >> 3) * 1024 + (tid & 7) * 8) * 2);
;   const u16* Ag = A + (size_t)m0 * 1024;
;   const u16* Bg = Bt + (size_t)n0 * 1024;
;   uint4 ra0, ra1, ra2, ra3, rb0, rb1, rb2, rb3;
;     ...
;   GLOAD(Ag, Bg, 0)
;   u16* As0 = (u16*)lds;
;   u16* Bs0 = As0 + 256 * 64;
;   u16* As1 = Bs0 + 256 * 64;
;   u16* Bs1 = As1 + 256 * 64;
;   const int lw = (tid >> 3) * 64 + (((tid & 7) ^ ((tid >> 3) & 7)) * 8);
;   GSTORE(As0, Bs0)
;   while (true) {
;   const int tn = t + 1;
;   int m1 = 0, n1 = 0;
;   const bool has_next = tile_coords<EPI>(tn, mpx, m1, n1);
;   const u16* Agn = A + (size_t)m1 * 1024;
;   const u16* Bgn = Bt + (size_t)n1 * 1024;
;   f32x4 acc[8][4];
; #pragma unroll
;   for (int i = 0; i < 8; ++i)
; #pragma unroll
;     for (int j = 0; j < 4; ++j) acc[i][j] = zero4();
;   {
;   const int lane = tid & 63, w = tid >> 6, r = lane & 15, g = lane >> 4, wm = w >> 2, wn = w & 3;
;   __syncthreads();
;   GLOAD(Ag, Bg, 64)
;   __builtin_amdgcn_sched_barrier(0);
;   GCOMPUTE_KS(As0, Bs0, 0)
;   __builtin_amdgcn_sched_barrier(0);
;   GSTORE(As1, Bs1)
;   GLOAD(Ag, Bg, 128)
;   __builtin_amdgcn_sched_barrier(0);
;   GCOMPUTE_KS(As0, Bs0, 1)
;   __builtin_amdgcn_sched_barrier(0);
.Ldephase_out_done:
	s_ashr_i32 s51, s50, 31
	s_lshl_b64 s[26:27], s[50:51], 21
	s_add_u32 s26, s14, s26
	v_readlane_b32 s40, v254, 11
	s_addc_u32 s27, s15, s27
	s_mul_i32 s51, s2, s40
	v_readlane_b32 s2, v254, 8
	s_add_u32 s46, s26, s2
	v_readlane_b32 s2, v254, 6
	s_addc_u32 s47, s27, 0
	s_add_i32 s2, s51, s2
	s_lshl_b32 s2, s2, 8
	s_lshl_b64 s[40:41], s[2:3], 11
	v_lshlrev_b32_e32 v2, 4, v0
	s_add_u32 s48, s16, s40
	v_ashrrev_i32_e32 v34, 3, v0
	v_and_b32_e32 v2, 0x70, v2
	s_addc_u32 s49, s17, s41
	v_lshl_or_b32 v196, v34, 11, v2
	v_mov_b32_e32 v197, v1
	v_lshl_add_u64 v[14:15], s[48:49], 0, v[196:197]
	v_add_co_u32_e32 v6, vcc, s33, v14
	global_load_dwordx4 v[2:5], v196, s[48:49]
	global_load_dwordx4 v[18:21], v196, s[46:47]
	v_addc_co_u32_e32 v7, vcc, 0, v15, vcc
	v_add_co_u32_e32 v10, vcc, s35, v14
	v_lshl_add_u64 v[30:31], s[46:47], 0, v[196:197]
	s_nop 0
	v_addc_co_u32_e32 v11, vcc, 0, v15, vcc
	v_add_co_u32_e32 v14, vcc, s39, v14
	global_load_dwordx4 v[6:9], v[6:7], off
	s_nop 0
	v_addc_co_u32_e32 v15, vcc, 0, v15, vcc
	v_add_co_u32_e32 v22, vcc, s33, v30
	global_load_dwordx4 v[10:13], v[10:11], off
	s_nop 0
	v_addc_co_u32_e32 v23, vcc, 0, v31, vcc
	global_load_dwordx4 v[14:17], v[14:15], off
	v_add_co_u32_e32 v26, vcc, s35, v30
	global_load_dwordx4 v[22:25], v[22:23], off
	s_nop 0
	v_addc_co_u32_e32 v27, vcc, 0, v31, vcc
	v_add_co_u32_e32 v30, vcc, s39, v30
	global_load_dwordx4 v[26:29], v[26:27], off
	s_nop 0
	v_addc_co_u32_e32 v31, vcc, 0, v31, vcc
	global_load_dwordx4 v[30:33], v[30:31], off
	v_xor_b32_e32 v35, v34, v0
	s_load_dword s40, s[76:77], 0x0
	v_lshlrev_b32_e32 v35, 4, v35
	v_and_b32_e32 v35, 0x70, v35
	v_lshl_or_b32 v34, v34, 7, v35
	v_add_u32_e32 v198, 32, v34
	s_waitcnt lgkmcnt(0)
	s_lshr_b32 s57, s40, 3
	v_readlane_b32 s40, v255, 23
	s_mov_b32 s56, 0
	v_add_u32_e32 v199, s78, v34
	v_add_u32_e32 v203, s40, v34
	s_mov_b32 s60, s2
	v_readlane_b32 s61, v254, 7
	s_waitcnt vmcnt(7)
	ds_write_b128 v198, v[2:5]
	s_waitcnt vmcnt(5)
	ds_write_b128 v198, v[6:9] offset:8192
	s_waitcnt vmcnt(4)
	ds_write_b128 v198, v[10:13] offset:16384
	s_waitcnt vmcnt(3)
	ds_write_b128 v198, v[14:17] offset:24576
	ds_write_b128 v198, v[18:21] offset:32768
	s_waitcnt vmcnt(2)
	ds_write_b128 v198, v[22:25] offset:40960
	s_waitcnt vmcnt(1)
	ds_write_b128 v198, v[26:29] offset:49152
	s_waitcnt vmcnt(0)
	s_mov_b32 s100, 1
	ds_write_b128 v198, v[30:33] offset:57344
	v_lshrrev_b32_e32 v2, 4, v0
	v_bfe_u32 v3, v0, 4, 2
	v_and_b32_e32 v4, 7, v0
	v_bitop3_b32 v2, v2, v4, 3 bitop3:0x6c
	v_add_u32_e32 v6, 0x2000, v34
	v_bitop3_b32 v3, v3, v4, 4 bitop3:0x36
	v_lshlrev_b32_e32 v2, 4, v2
	v_add_u32_e32 v200, s78, v6
	v_add_u32_e32 v7, 0x4000, v34
	v_add_u32_e32 v204, s40, v6
	v_lshlrev_b32_e32 v3, 4, v3
	v_lshlrev_b32_e32 v6, 7, v0
	v_lshlrev_b32_e32 v0, 6, v0
	v_add_u32_e32 v5, 32, v2
	v_add_u32_e32 v201, s78, v7
	v_add_u32_e32 v8, 0x6000, v34
	v_add_u32_e32 v205, s40, v7
	v_add_u32_e32 v4, 32, v3
	v_and_b32_e32 v7, 0x6000, v6
	v_and_b32_e32 v0, 0xffffc000, v0
	v_add_u32_e32 v202, s78, v8
	v_add_u32_e32 v206, s40, v8
	v_and_b32_e32 v6, 0x780, v6
	v_add_u32_e32 v8, v5, v7
	v_add_u32_e32 v5, v5, v0
	v_add_u32_e32 v9, v4, v7
	v_add_u32_e32 v4, v4, v0
	v_add3_u32 v10, s40, v2, v7
	v_add3_u32 v2, s78, v2, v0
	v_add3_u32 v7, s40, v3, v7
	v_add3_u32 v0, s78, v3, v0
	v_add_u32_e32 v207, v8, v6
	v_add_u32_e32 v227, v5, v6
	v_add_u32_e32 v228, v9, v6
	v_add_u32_e32 v229, v4, v6
	v_add_u32_e32 v230, v10, v6
	v_add_u32_e32 v231, v2, v6
	v_add_u32_e32 v232, v7, v6
	v_add_u32_e32 v233, v0, v6
.LBB0_69:
	s_add_i32 s56, s56, 1
	s_mul_i32 s2, s56, s57
	s_add_i32 s2, s2, s84
	s_cmp_ge_u32 s2, s25
	s_cselect_b64 s[40:41], -1, 0
	s_lshr_b32 s42, s2, 2
	s_add_i32 s42, s42, s51
	s_lshl_b32 s58, s42, 8
	s_lshl_b32 s42, s2, 8
	s_and_b32 s59, s42, 0x300
	s_lshl_b32 s42, s59, 11
	s_cmp_lt_u32 s2, s25
	s_cselect_b32 s2, s58, 0
	s_cselect_b32 s44, s42, 0
	s_lshl_b64 s[42:43], s[2:3], 11
	s_add_u32 s42, s16, s42
	s_addc_u32 s43, s17, s43
	s_add_u32 s44, s26, s44
	s_addc_u32 s45, s27, 0
	v_lshrrev_b32_e32 v106, 3, v195
	v_and_b32_e32 v107, 7, v195
	v_and_b32_e32 v108, 7, v106
	v_xor_b32_e32 v107, v107, v108
	v_lshlrev_b32_e32 v107, 4, v107
	v_lshl_or_b32 v102, v106, 11, v107
	v_add_u32_e32 v103, s33, v102
	v_add_u32_e32 v104, s35, v102
	v_add_u32_e32 v105, s39, v102
	v_readfirstlane_b32 s62, v195
	s_lshr_b32 s62, s62, 6
	s_lshl_b32 s62, s62, 10
	s_and_b32 s63, s84, 7
	s_lshl_b32 s63, s63, 1
	s_mov_b32 s64, 0
	s_waitcnt lgkmcnt(0)
	s_barrier
	s_cmp_eq_u32 s100, 0
	s_cbranch_scc1 .Lrot_out_nofirst
	s_mov_b32 s100, 0
	s_lshl_b32 s2, s63, 7
	s_add_u32 s54, s48, s2
	s_addc_u32 s55, s49, 0
	s_add_u32 s52, s46, s2
	s_addc_u32 s53, s47, 0
	s_add_i32 m0, s62, 0x20
	s_nop 0
	global_load_lds_dwordx4 v102, s[54:55]
	s_add_i32 m0, s62, 0x2020
	s_nop 0
	global_load_lds_dwordx4 v103, s[54:55]
	s_add_i32 m0, s62, 0x4020
	s_nop 0
	global_load_lds_dwordx4 v104, s[54:55]
	s_add_i32 m0, s62, 0x6020
	s_nop 0
	global_load_lds_dwordx4 v105, s[54:55]
	s_add_i32 m0, s62, 0x8020
	s_nop 0
	global_load_lds_dwordx4 v102, s[52:53]
	s_add_i32 m0, s62, 0xa020
	s_nop 0
	global_load_lds_dwordx4 v103, s[52:53]
	s_add_i32 m0, s62, 0xc020
	s_nop 0
	global_load_lds_dwordx4 v104, s[52:53]
	s_add_i32 m0, s62, 0xe020
	s_nop 0
	global_load_lds_dwordx4 v105, s[52:53]
	s_waitcnt vmcnt(0)
	s_barrier
; #define GCOMPUTE(AS, BS) GCOMPUTE_KS(AS, BS, 0) GCOMPUTE_KS(AS, BS, 1)
; template <int EPI>
; DI void gemm_phase(const P& p, int l, const u16* __restrict__ A, const u16* __restrict__ Bt, int mpx, char* lds) {
;     ...
; #pragma unroll 1
;   for (int kk = 1; kk < 15; kk += 2) {
;     __syncthreads();
;     GSTORE(As0, Bs0)
;     GLOAD(Ag, Bg, (kk + 2) * 64)
;     __builtin_amdgcn_sched_barrier(0);
;     GCOMPUTE(As1, Bs1)
;     __builtin_amdgcn_sched_barrier(0);
.Lrot_out_nofirst:
	s_add_i32 s63, s63, 1
	s_and_b32 s63, s63, 15
	s_lshl_b32 s2, s63, 7
	s_add_u32 s54, s48, s2
	s_addc_u32 s55, s49, 0
	s_add_u32 s52, s46, s2
	s_addc_u32 s53, s47, 0
	ds_read_b128 v[212:215], v207 offset:32768
	ds_read_b128 v[216:219], v207 offset:34816
	ds_read_b128 v[220:223], v207 offset:36864
	ds_read_b128 v[234:237], v207 offset:38912
	ds_read_b128 v[238:241], v227
	ds_read_b128 v[242:245], v227 offset:2048
	ds_read_b128 v[246:249], v227 offset:4096
	ds_read_b128 v[250:253], v227 offset:6144
	s_waitcnt lgkmcnt(3)
	v_mfma_f32_16x16x32_bf16 v[6:9], v[238:241], v[212:215], 0
	v_mfma_f32_16x16x32_bf16 v[10:13], v[238:241], v[216:219], 0
	v_mfma_f32_16x16x32_bf16 v[14:17], v[238:241], v[220:223], 0
	v_mfma_f32_16x16x32_bf16 v[22:25], v[238:241], v[234:237], 0
	ds_read_b128 v[238:241], v227 offset:8192
	s_add_i32 m0, s62, 0x10020
	s_nop 0
	global_load_lds_dwordx4 v102, s[54:55]
	s_add_i32 m0, s62, 0x12020
	s_nop 0
	global_load_lds_dwordx4 v103, s[54:55]
	s_waitcnt lgkmcnt(3)
	v_mfma_f32_16x16x32_bf16 v[26:29], v[242:245], v[212:215], 0
	v_mfma_f32_16x16x32_bf16 v[30:33], v[242:245], v[216:219], 0
	v_mfma_f32_16x16x32_bf16 v[34:37], v[242:245], v[220:223], 0
	v_mfma_f32_16x16x32_bf16 v[38:41], v[242:245], v[234:237], 0
	ds_read_b128 v[242:245], v227 offset:10240
	ds_read_b128 v[86:89], v228 offset:32768
	s_add_i32 m0, s62, 0x14020
	s_nop 0
	global_load_lds_dwordx4 v104, s[54:55]
	s_add_i32 m0, s62, 0x16020
	s_nop 0
	global_load_lds_dwordx4 v105, s[54:55]
	s_waitcnt lgkmcnt(4)
	v_mfma_f32_16x16x32_bf16 v[42:45], v[246:249], v[212:215], 0
	v_mfma_f32_16x16x32_bf16 v[46:49], v[246:249], v[216:219], 0
	v_mfma_f32_16x16x32_bf16 v[50:53], v[246:249], v[220:223], 0
	v_mfma_f32_16x16x32_bf16 v[54:57], v[246:249], v[234:237], 0
	ds_read_b128 v[246:249], v227 offset:12288
	ds_read_b128 v[90:93], v228 offset:34816
	s_add_i32 m0, s62, 0x18020
	s_nop 0
	global_load_lds_dwordx4 v102, s[52:53]
	s_add_i32 m0, s62, 0x1a020
	s_nop 0
	global_load_lds_dwordx4 v103, s[52:53]
	s_waitcnt lgkmcnt(5)
	v_mfma_f32_16x16x32_bf16 v[58:61], v[250:253], v[212:215], 0
	v_mfma_f32_16x16x32_bf16 v[62:65], v[250:253], v[216:219], 0
	v_mfma_f32_16x16x32_bf16 v[66:69], v[250:253], v[220:223], 0
	v_mfma_f32_16x16x32_bf16 v[70:73], v[250:253], v[234:237], 0
	ds_read_b128 v[250:253], v227 offset:14336
	ds_read_b128 v[94:97], v228 offset:36864
	s_add_i32 m0, s62, 0x1c020
	s_nop 0
	global_load_lds_dwordx4 v104, s[52:53]
	s_add_i32 m0, s62, 0x1e020
	s_nop 0
	global_load_lds_dwordx4 v105, s[52:53]
	s_waitcnt lgkmcnt(6)
	v_mfma_f32_16x16x32_bf16 v[74:77], v[238:241], v[212:215], 0
	v_mfma_f32_16x16x32_bf16 v[78:81], v[238:241], v[216:219], 0
	v_mfma_f32_16x16x32_bf16 v[82:85], v[238:241], v[220:223], 0
	v_mfma_f32_16x16x32_bf16 v[114:117], v[238:241], v[234:237], 0
	ds_read_b128 v[238:241], v229
	ds_read_b128 v[98:101], v228 offset:38912
	s_waitcnt lgkmcnt(7)
	v_mfma_f32_16x16x32_bf16 v[118:121], v[242:245], v[212:215], 0
	v_mfma_f32_16x16x32_bf16 v[122:125], v[242:245], v[216:219], 0
	v_mfma_f32_16x16x32_bf16 v[126:129], v[242:245], v[220:223], 0
	v_mfma_f32_16x16x32_bf16 v[130:133], v[242:245], v[234:237], 0
	ds_read_b128 v[242:245], v229 offset:2048
	s_waitcnt lgkmcnt(6)
	v_mfma_f32_16x16x32_bf16 v[134:137], v[246:249], v[212:215], 0
	v_mfma_f32_16x16x32_bf16 v[138:141], v[246:249], v[216:219], 0
	v_mfma_f32_16x16x32_bf16 v[142:145], v[246:249], v[220:223], 0
	v_mfma_f32_16x16x32_bf16 v[146:149], v[246:249], v[234:237], 0
	ds_read_b128 v[246:249], v229 offset:4096
	s_waitcnt lgkmcnt(5)
	v_mfma_f32_16x16x32_bf16 v[150:153], v[250:253], v[212:215], 0
	v_mfma_f32_16x16x32_bf16 v[154:157], v[250:253], v[216:219], 0
	v_mfma_f32_16x16x32_bf16 v[158:161], v[250:253], v[220:223], 0
	v_mfma_f32_16x16x32_bf16 v[2:5], v[250:253], v[234:237], 0
	ds_read_b128 v[250:253], v229 offset:6144
	s_waitcnt lgkmcnt(3)
	v_mfma_f32_16x16x32_bf16 v[6:9], v[238:241], v[86:89], v[6:9]
	v_mfma_f32_16x16x32_bf16 v[10:13], v[238:241], v[90:93], v[10:13]
	v_mfma_f32_16x16x32_bf16 v[14:17], v[238:241], v[94:97], v[14:17]
	v_mfma_f32_16x16x32_bf16 v[22:25], v[238:241], v[98:101], v[22:25]
	ds_read_b128 v[238:241], v229 offset:8192
	s_waitcnt lgkmcnt(3)
	v_mfma_f32_16x16x32_bf16 v[26:29], v[242:245], v[86:89], v[26:29]
	v_mfma_f32_16x16x32_bf16 v[30:33], v[242:245], v[90:93], v[30:33]
	v_mfma_f32_16x16x32_bf16 v[34:37], v[242:245], v[94:97], v[34:37]
	v_mfma_f32_16x16x32_bf16 v[38:41], v[242:245], v[98:101], v[38:41]
	ds_read_b128 v[242:245], v229 offset:10240
	s_waitcnt lgkmcnt(3)
	v_mfma_f32_16x16x32_bf16 v[42:45], v[246:249], v[86:89], v[42:45]
	v_mfma_f32_16x16x32_bf16 v[46:49], v[246:249], v[90:93], v[46:49]
	v_mfma_f32_16x16x32_bf16 v[50:53], v[246:249], v[94:97], v[50:53]
	v_mfma_f32_16x16x32_bf16 v[54:57], v[246:249], v[98:101], v[54:57]
	ds_read_b128 v[246:249], v229 offset:12288
	s_waitcnt lgkmcnt(3)
	v_mfma_f32_16x16x32_bf16 v[58:61], v[250:253], v[86:89], v[58:61]
	v_mfma_f32_16x16x32_bf16 v[62:65], v[250:253], v[90:93], v[62:65]
	v_mfma_f32_16x16x32_bf16 v[66:69], v[250:253], v[94:97], v[66:69]
	v_mfma_f32_16x16x32_bf16 v[70:73], v[250:253], v[98:101], v[70:73]
	ds_read_b128 v[250:253], v229 offset:14336
	s_waitcnt lgkmcnt(3)
	v_mfma_f32_16x16x32_bf16 v[74:77], v[238:241], v[86:89], v[74:77]
	v_mfma_f32_16x16x32_bf16 v[78:81], v[238:241], v[90:93], v[78:81]
	v_mfma_f32_16x16x32_bf16 v[82:85], v[238:241], v[94:97], v[82:85]
	v_mfma_f32_16x16x32_bf16 v[114:117], v[238:241], v[98:101], v[114:117]
	s_waitcnt lgkmcnt(2)
	v_mfma_f32_16x16x32_bf16 v[118:121], v[242:245], v[86:89], v[118:121]
	v_mfma_f32_16x16x32_bf16 v[122:125], v[242:245], v[90:93], v[122:125]
	v_mfma_f32_16x16x32_bf16 v[126:129], v[242:245], v[94:97], v[126:129]
	v_mfma_f32_16x16x32_bf16 v[130:133], v[242:245], v[98:101], v[130:133]
	s_waitcnt lgkmcnt(0)
	s_waitcnt vmcnt(0)
	s_add_i32 s63, s63, 1
	s_and_b32 s63, s63, 15
	s_lshl_b32 s2, s63, 7
	s_add_u32 s54, s48, s2
	s_addc_u32 s55, s49, 0
	s_add_u32 s52, s46, s2
	s_addc_u32 s53, s47, 0
	s_barrier
	ds_read_b128 v[212:215], v230
	ds_read_b128 v[216:219], v230 offset:2048
	ds_read_b128 v[220:223], v230 offset:4096
	ds_read_b128 v[234:237], v230 offset:6144
	ds_read_b128 v[238:241], v231
	ds_read_b128 v[242:245], v231 offset:2048
	v_mfma_f32_16x16x32_bf16 v[134:137], v[246:249], v[86:89], v[134:137]
	v_mfma_f32_16x16x32_bf16 v[138:141], v[246:249], v[90:93], v[138:141]
	v_mfma_f32_16x16x32_bf16 v[142:145], v[246:249], v[94:97], v[142:145]
	v_mfma_f32_16x16x32_bf16 v[146:149], v[246:249], v[98:101], v[146:149]
	ds_read_b128 v[246:249], v231 offset:4096
	v_mfma_f32_16x16x32_bf16 v[150:153], v[250:253], v[86:89], v[150:153]
	v_mfma_f32_16x16x32_bf16 v[154:157], v[250:253], v[90:93], v[154:157]
	v_mfma_f32_16x16x32_bf16 v[158:161], v[250:253], v[94:97], v[158:161]
	v_mfma_f32_16x16x32_bf16 v[2:5], v[250:253], v[98:101], v[2:5]
	ds_read_b128 v[250:253], v231 offset:6144
; #define GCOMPUTE(AS, BS) GCOMPUTE_KS(AS, BS, 0) GCOMPUTE_KS(AS, BS, 1)
; template <int EPI>
; DI void gemm_phase(const P& p, int l, const u16* __restrict__ A, const u16* __restrict__ Bt, int mpx, char* lds) {
;     ...
;   for (int kk = 1; kk < 15; kk += 2) {
;     __syncthreads();
;     GSTORE(As0, Bs0)
;     GLOAD(Ag, Bg, (kk + 2) * 64)
;     __builtin_amdgcn_sched_barrier(0);
;     GCOMPUTE(As1, Bs1)
;     __builtin_amdgcn_sched_barrier(0);
;     __syncthreads();
;     GSTORE(As1, Bs1)
;     {
;       const bool in_tile = kk + 3 < 16;
;       const u16* pa = in_tile ? Ag : Agn;
;       const u16* pb = in_tile ? Bg : Bgn;
;       const int k0 = in_tile ? (kk + 3) * 64 : 0;
;       GLOAD(pa, pb, k0)
;     }
;     __builtin_amdgcn_sched_barrier(0);
;     GCOMPUTE(As0, Bs0)
;     __builtin_amdgcn_sched_barrier(0);
.LBB0_70:
	s_waitcnt lgkmcnt(3)
	v_mfma_f32_16x16x32_bf16 v[6:9], v[238:241], v[212:215], v[6:9]
	v_mfma_f32_16x16x32_bf16 v[10:13], v[238:241], v[216:219], v[10:13]
	v_mfma_f32_16x16x32_bf16 v[14:17], v[238:241], v[220:223], v[14:17]
	v_mfma_f32_16x16x32_bf16 v[22:25], v[238:241], v[234:237], v[22:25]
	ds_read_b128 v[238:241], v231 offset:8192
	s_add_i32 m0, s62, 0x20
	s_nop 0
	global_load_lds_dwordx4 v102, s[54:55]
	s_add_i32 m0, s62, 0x2020
	s_nop 0
	global_load_lds_dwordx4 v103, s[54:55]
	s_waitcnt lgkmcnt(3)
	v_mfma_f32_16x16x32_bf16 v[26:29], v[242:245], v[212:215], v[26:29]
	v_mfma_f32_16x16x32_bf16 v[30:33], v[242:245], v[216:219], v[30:33]
	v_mfma_f32_16x16x32_bf16 v[34:37], v[242:245], v[220:223], v[34:37]
	v_mfma_f32_16x16x32_bf16 v[38:41], v[242:245], v[234:237], v[38:41]
	ds_read_b128 v[242:245], v231 offset:10240
	ds_read_b128 v[86:89], v232
	s_add_i32 m0, s62, 0x4020
	s_nop 0
	global_load_lds_dwordx4 v104, s[54:55]
	s_add_i32 m0, s62, 0x6020
	s_nop 0
	global_load_lds_dwordx4 v105, s[54:55]
	s_waitcnt lgkmcnt(4)
	v_mfma_f32_16x16x32_bf16 v[42:45], v[246:249], v[212:215], v[42:45]
	v_mfma_f32_16x16x32_bf16 v[46:49], v[246:249], v[216:219], v[46:49]
	v_mfma_f32_16x16x32_bf16 v[50:53], v[246:249], v[220:223], v[50:53]
	v_mfma_f32_16x16x32_bf16 v[54:57], v[246:249], v[234:237], v[54:57]
	ds_read_b128 v[246:249], v231 offset:12288
	ds_read_b128 v[90:93], v232 offset:2048
	s_add_i32 m0, s62, 0x8020
	s_nop 0
	global_load_lds_dwordx4 v102, s[52:53]
	s_add_i32 m0, s62, 0xa020
	s_nop 0
	global_load_lds_dwordx4 v103, s[52:53]
	s_waitcnt lgkmcnt(5)
	v_mfma_f32_16x16x32_bf16 v[58:61], v[250:253], v[212:215], v[58:61]
	v_mfma_f32_16x16x32_bf16 v[62:65], v[250:253], v[216:219], v[62:65]
	v_mfma_f32_16x16x32_bf16 v[66:69], v[250:253], v[220:223], v[66:69]
	v_mfma_f32_16x16x32_bf16 v[70:73], v[250:253], v[234:237], v[70:73]
	ds_read_b128 v[250:253], v231 offset:14336
	ds_read_b128 v[94:97], v232 offset:4096
	s_add_i32 m0, s62, 0xc020
	s_nop 0
	global_load_lds_dwordx4 v104, s[52:53]
	s_add_i32 m0, s62, 0xe020
	s_nop 0
	global_load_lds_dwordx4 v105, s[52:53]
	s_waitcnt lgkmcnt(6)
	v_mfma_f32_16x16x32_bf16 v[74:77], v[238:241], v[212:215], v[74:77]
	v_mfma_f32_16x16x32_bf16 v[78:81], v[238:241], v[216:219], v[78:81]
	v_mfma_f32_16x16x32_bf16 v[82:85], v[238:241], v[220:223], v[82:85]
	v_mfma_f32_16x16x32_bf16 v[114:117], v[238:241], v[234:237], v[114:117]
	ds_read_b128 v[238:241], v233
	ds_read_b128 v[98:101], v232 offset:6144
	s_waitcnt lgkmcnt(7)
	v_mfma_f32_16x16x32_bf16 v[118:121], v[242:245], v[212:215], v[118:121]
	v_mfma_f32_16x16x32_bf16 v[122:125], v[242:245], v[216:219], v[122:125]
	v_mfma_f32_16x16x32_bf16 v[126:129], v[242:245], v[220:223], v[126:129]
	v_mfma_f32_16x16x32_bf16 v[130:133], v[242:245], v[234:237], v[130:133]
	ds_read_b128 v[242:245], v233 offset:2048
	s_waitcnt lgkmcnt(6)
	v_mfma_f32_16x16x32_bf16 v[134:137], v[246:249], v[212:215], v[134:137]
	v_mfma_f32_16x16x32_bf16 v[138:141], v[246:249], v[216:219], v[138:141]
	v_mfma_f32_16x16x32_bf16 v[142:145], v[246:249], v[220:223], v[142:145]
	v_mfma_f32_16x16x32_bf16 v[146:149], v[246:249], v[234:237], v[146:149]
	ds_read_b128 v[246:249], v233 offset:4096
	s_waitcnt lgkmcnt(5)
	v_mfma_f32_16x16x32_bf16 v[150:153], v[250:253], v[212:215], v[150:153]
	v_mfma_f32_16x16x32_bf16 v[154:157], v[250:253], v[216:219], v[154:157]
	v_mfma_f32_16x16x32_bf16 v[158:161], v[250:253], v[220:223], v[158:161]
	v_mfma_f32_16x16x32_bf16 v[2:5], v[250:253], v[234:237], v[2:5]
	ds_read_b128 v[250:253], v233 offset:6144
	s_waitcnt lgkmcnt(3)
	v_mfma_f32_16x16x32_bf16 v[6:9], v[238:241], v[86:89], v[6:9]
	v_mfma_f32_16x16x32_bf16 v[10:13], v[238:241], v[90:93], v[10:13]
	v_mfma_f32_16x16x32_bf16 v[14:17], v[238:241], v[94:97], v[14:17]
	v_mfma_f32_16x16x32_bf16 v[22:25], v[238:241], v[98:101], v[22:25]
	ds_read_b128 v[238:241], v233 offset:8192
	s_waitcnt lgkmcnt(3)
	v_mfma_f32_16x16x32_bf16 v[26:29], v[242:245], v[86:89], v[26:29]
	v_mfma_f32_16x16x32_bf16 v[30:33], v[242:245], v[90:93], v[30:33]
	v_mfma_f32_16x16x32_bf16 v[34:37], v[242:245], v[94:97], v[34:37]
	v_mfma_f32_16x16x32_bf16 v[38:41], v[242:245], v[98:101], v[38:41]
	ds_read_b128 v[242:245], v233 offset:10240
	s_waitcnt lgkmcnt(3)
	v_mfma_f32_16x16x32_bf16 v[42:45], v[246:249], v[86:89], v[42:45]
	v_mfma_f32_16x16x32_bf16 v[46:49], v[246:249], v[90:93], v[46:49]
	v_mfma_f32_16x16x32_bf16 v[50:53], v[246:249], v[94:97], v[50:53]
	v_mfma_f32_16x16x32_bf16 v[54:57], v[246:249], v[98:101], v[54:57]
	ds_read_b128 v[246:249], v233 offset:12288
	s_waitcnt lgkmcnt(3)
	v_mfma_f32_16x16x32_bf16 v[58:61], v[250:253], v[86:89], v[58:61]
	v_mfma_f32_16x16x32_bf16 v[62:65], v[250:253], v[90:93], v[62:65]
	v_mfma_f32_16x16x32_bf16 v[66:69], v[250:253], v[94:97], v[66:69]
	v_mfma_f32_16x16x32_bf16 v[70:73], v[250:253], v[98:101], v[70:73]
	ds_read_b128 v[250:253], v233 offset:14336
	s_waitcnt lgkmcnt(3)
	v_mfma_f32_16x16x32_bf16 v[74:77], v[238:241], v[86:89], v[74:77]
	v_mfma_f32_16x16x32_bf16 v[78:81], v[238:241], v[90:93], v[78:81]
	v_mfma_f32_16x16x32_bf16 v[82:85], v[238:241], v[94:97], v[82:85]
	v_mfma_f32_16x16x32_bf16 v[114:117], v[238:241], v[98:101], v[114:117]
	s_waitcnt lgkmcnt(2)
	v_mfma_f32_16x16x32_bf16 v[118:121], v[242:245], v[86:89], v[118:121]
	v_mfma_f32_16x16x32_bf16 v[122:125], v[242:245], v[90:93], v[122:125]
	v_mfma_f32_16x16x32_bf16 v[126:129], v[242:245], v[94:97], v[126:129]
	v_mfma_f32_16x16x32_bf16 v[130:133], v[242:245], v[98:101], v[130:133]
	s_waitcnt lgkmcnt(0)
	s_waitcnt vmcnt(0)
	s_add_i32 s63, s63, 1
	s_and_b32 s63, s63, 15
	s_lshl_b32 s2, s63, 7
	s_add_u32 s54, s48, s2
	s_addc_u32 s55, s49, 0
	s_add_u32 s52, s46, s2
	s_addc_u32 s53, s47, 0
	s_barrier
; #define GCOMPUTE(AS, BS) GCOMPUTE_KS(AS, BS, 0) GCOMPUTE_KS(AS, BS, 1)
; template <int EPI>
; DI void gemm_phase(const P& p, int l, const u16* __restrict__ A, const u16* __restrict__ Bt, int mpx, char* lds) {
;     ...
;   for (int kk = 1; kk < 15; kk += 2) {
;     __syncthreads();
;     GSTORE(As0, Bs0)
;     GLOAD(Ag, Bg, (kk + 2) * 64)
;     __builtin_amdgcn_sched_barrier(0);
;     GCOMPUTE(As1, Bs1)
;     __builtin_amdgcn_sched_barrier(0);
;     __syncthreads();
;     GSTORE(As1, Bs1)
;     {
;       const bool in_tile = kk + 3 < 16;
;       const u16* pa = in_tile ? Ag : Agn;
;       const u16* pb = in_tile ? Bg : Bgn;
;       const int k0 = in_tile ? (kk + 3) * 64 : 0;
;       GLOAD(pa, pb, k0)
;     }
;     __builtin_amdgcn_sched_barrier(0);
;     GCOMPUTE(As0, Bs0)
;     __builtin_amdgcn_sched_barrier(0);
	ds_read_b128 v[212:215], v207 offset:32768
	ds_read_b128 v[216:219], v207 offset:34816
	ds_read_b128 v[220:223], v207 offset:36864
	ds_read_b128 v[234:237], v207 offset:38912
	ds_read_b128 v[238:241], v227
	ds_read_b128 v[242:245], v227 offset:2048
	v_mfma_f32_16x16x32_bf16 v[134:137], v[246:249], v[86:89], v[134:137]
	v_mfma_f32_16x16x32_bf16 v[138:141], v[246:249], v[90:93], v[138:141]
	v_mfma_f32_16x16x32_bf16 v[142:145], v[246:249], v[94:97], v[142:145]
	v_mfma_f32_16x16x32_bf16 v[146:149], v[246:249], v[98:101], v[146:149]
	ds_read_b128 v[246:249], v227 offset:4096
	v_mfma_f32_16x16x32_bf16 v[150:153], v[250:253], v[86:89], v[150:153]
	v_mfma_f32_16x16x32_bf16 v[154:157], v[250:253], v[90:93], v[154:157]
	v_mfma_f32_16x16x32_bf16 v[158:161], v[250:253], v[94:97], v[158:161]
	v_mfma_f32_16x16x32_bf16 v[2:5], v[250:253], v[98:101], v[2:5]
	ds_read_b128 v[250:253], v227 offset:6144
	s_waitcnt lgkmcnt(3)
	v_mfma_f32_16x16x32_bf16 v[6:9], v[238:241], v[212:215], v[6:9]
	v_mfma_f32_16x16x32_bf16 v[10:13], v[238:241], v[216:219], v[10:13]
	v_mfma_f32_16x16x32_bf16 v[14:17], v[238:241], v[220:223], v[14:17]
	v_mfma_f32_16x16x32_bf16 v[22:25], v[238:241], v[234:237], v[22:25]
	ds_read_b128 v[238:241], v227 offset:8192
	s_add_i32 m0, s62, 0x10020
	s_nop 0
	global_load_lds_dwordx4 v102, s[54:55]
	s_add_i32 m0, s62, 0x12020
	s_nop 0
	global_load_lds_dwordx4 v103, s[54:55]
	s_waitcnt lgkmcnt(3)
	v_mfma_f32_16x16x32_bf16 v[26:29], v[242:245], v[212:215], v[26:29]
	v_mfma_f32_16x16x32_bf16 v[30:33], v[242:245], v[216:219], v[30:33]
	v_mfma_f32_16x16x32_bf16 v[34:37], v[242:245], v[220:223], v[34:37]
	v_mfma_f32_16x16x32_bf16 v[38:41], v[242:245], v[234:237], v[38:41]
	ds_read_b128 v[242:245], v227 offset:10240
	ds_read_b128 v[86:89], v228 offset:32768
	s_add_i32 m0, s62, 0x14020
	s_nop 0
	global_load_lds_dwordx4 v104, s[54:55]
	s_add_i32 m0, s62, 0x16020
	s_nop 0
	global_load_lds_dwordx4 v105, s[54:55]
	s_waitcnt lgkmcnt(4)
	v_mfma_f32_16x16x32_bf16 v[42:45], v[246:249], v[212:215], v[42:45]
	v_mfma_f32_16x16x32_bf16 v[46:49], v[246:249], v[216:219], v[46:49]
	v_mfma_f32_16x16x32_bf16 v[50:53], v[246:249], v[220:223], v[50:53]
	v_mfma_f32_16x16x32_bf16 v[54:57], v[246:249], v[234:237], v[54:57]
	ds_read_b128 v[246:249], v227 offset:12288
	ds_read_b128 v[90:93], v228 offset:34816
	s_add_i32 m0, s62, 0x18020
	s_nop 0
	global_load_lds_dwordx4 v102, s[52:53]
	s_add_i32 m0, s62, 0x1a020
	s_nop 0
	global_load_lds_dwordx4 v103, s[52:53]
	s_waitcnt lgkmcnt(5)
	v_mfma_f32_16x16x32_bf16 v[58:61], v[250:253], v[212:215], v[58:61]
	v_mfma_f32_16x16x32_bf16 v[62:65], v[250:253], v[216:219], v[62:65]
	v_mfma_f32_16x16x32_bf16 v[66:69], v[250:253], v[220:223], v[66:69]
	v_mfma_f32_16x16x32_bf16 v[70:73], v[250:253], v[234:237], v[70:73]
	ds_read_b128 v[250:253], v227 offset:14336
	ds_read_b128 v[94:97], v228 offset:36864
	s_add_i32 m0, s62, 0x1c020
	s_nop 0
	global_load_lds_dwordx4 v104, s[52:53]
	s_add_i32 m0, s62, 0x1e020
	s_nop 0
	global_load_lds_dwordx4 v105, s[52:53]
	s_waitcnt lgkmcnt(6)
	v_mfma_f32_16x16x32_bf16 v[74:77], v[238:241], v[212:215], v[74:77]
	v_mfma_f32_16x16x32_bf16 v[78:81], v[238:241], v[216:219], v[78:81]
	v_mfma_f32_16x16x32_bf16 v[82:85], v[238:241], v[220:223], v[82:85]
	v_mfma_f32_16x16x32_bf16 v[114:117], v[238:241], v[234:237], v[114:117]
	ds_read_b128 v[238:241], v229
	ds_read_b128 v[98:101], v228 offset:38912
	s_waitcnt lgkmcnt(7)
	v_mfma_f32_16x16x32_bf16 v[118:121], v[242:245], v[212:215], v[118:121]
	v_mfma_f32_16x16x32_bf16 v[122:125], v[242:245], v[216:219], v[122:125]
	v_mfma_f32_16x16x32_bf16 v[126:129], v[242:245], v[220:223], v[126:129]
	v_mfma_f32_16x16x32_bf16 v[130:133], v[242:245], v[234:237], v[130:133]
	ds_read_b128 v[242:245], v229 offset:2048
	s_waitcnt lgkmcnt(6)
	v_mfma_f32_16x16x32_bf16 v[134:137], v[246:249], v[212:215], v[134:137]
	v_mfma_f32_16x16x32_bf16 v[138:141], v[246:249], v[216:219], v[138:141]
	v_mfma_f32_16x16x32_bf16 v[142:145], v[246:249], v[220:223], v[142:145]
	v_mfma_f32_16x16x32_bf16 v[146:149], v[246:249], v[234:237], v[146:149]
	ds_read_b128 v[246:249], v229 offset:4096
	s_waitcnt lgkmcnt(5)
	v_mfma_f32_16x16x32_bf16 v[150:153], v[250:253], v[212:215], v[150:153]
	v_mfma_f32_16x16x32_bf16 v[154:157], v[250:253], v[216:219], v[154:157]
	v_mfma_f32_16x16x32_bf16 v[158:161], v[250:253], v[220:223], v[158:161]
	v_mfma_f32_16x16x32_bf16 v[2:5], v[250:253], v[234:237], v[2:5]
	ds_read_b128 v[250:253], v229 offset:6144
	s_waitcnt lgkmcnt(3)
	v_mfma_f32_16x16x32_bf16 v[6:9], v[238:241], v[86:89], v[6:9]
	v_mfma_f32_16x16x32_bf16 v[10:13], v[238:241], v[90:93], v[10:13]
	v_mfma_f32_16x16x32_bf16 v[14:17], v[238:241], v[94:97], v[14:17]
	v_mfma_f32_16x16x32_bf16 v[22:25], v[238:241], v[98:101], v[22:25]
	ds_read_b128 v[238:241], v229 offset:8192
	s_waitcnt lgkmcnt(3)
	v_mfma_f32_16x16x32_bf16 v[26:29], v[242:245], v[86:89], v[26:29]
	v_mfma_f32_16x16x32_bf16 v[30:33], v[242:245], v[90:93], v[30:33]
	v_mfma_f32_16x16x32_bf16 v[34:37], v[242:245], v[94:97], v[34:37]
	v_mfma_f32_16x16x32_bf16 v[38:41], v[242:245], v[98:101], v[38:41]
	ds_read_b128 v[242:245], v229 offset:10240
	s_waitcnt lgkmcnt(3)
	v_mfma_f32_16x16x32_bf16 v[42:45], v[246:249], v[86:89], v[42:45]
	v_mfma_f32_16x16x32_bf16 v[46:49], v[246:249], v[90:93], v[46:49]
	v_mfma_f32_16x16x32_bf16 v[50:53], v[246:249], v[94:97], v[50:53]
	v_mfma_f32_16x16x32_bf16 v[54:57], v[246:249], v[98:101], v[54:57]
	ds_read_b128 v[246:249], v229 offset:12288
	s_waitcnt lgkmcnt(3)
	v_mfma_f32_16x16x32_bf16 v[58:61], v[250:253], v[86:89], v[58:61]
	v_mfma_f32_16x16x32_bf16 v[62:65], v[250:253], v[90:93], v[62:65]
	v_mfma_f32_16x16x32_bf16 v[66:69], v[250:253], v[94:97], v[66:69]
	v_mfma_f32_16x16x32_bf16 v[70:73], v[250:253], v[98:101], v[70:73]
	ds_read_b128 v[250:253], v229 offset:14336
	s_waitcnt lgkmcnt(3)
	v_mfma_f32_16x16x32_bf16 v[74:77], v[238:241], v[86:89], v[74:77]
	v_mfma_f32_16x16x32_bf16 v[78:81], v[238:241], v[90:93], v[78:81]
	v_mfma_f32_16x16x32_bf16 v[82:85], v[238:241], v[94:97], v[82:85]
	v_mfma_f32_16x16x32_bf16 v[114:117], v[238:241], v[98:101], v[114:117]
	s_waitcnt lgkmcnt(2)
	v_mfma_f32_16x16x32_bf16 v[118:121], v[242:245], v[86:89], v[118:121]
	v_mfma_f32_16x16x32_bf16 v[122:125], v[242:245], v[90:93], v[122:125]
	v_mfma_f32_16x16x32_bf16 v[126:129], v[242:245], v[94:97], v[126:129]
	v_mfma_f32_16x16x32_bf16 v[130:133], v[242:245], v[98:101], v[130:133]
	s_waitcnt lgkmcnt(0)
	s_waitcnt vmcnt(0)
	s_add_i32 s63, s63, 1
	s_and_b32 s63, s63, 15
	s_lshl_b32 s2, s63, 7
	s_add_u32 s54, s48, s2
	s_addc_u32 s55, s49, 0
	s_add_u32 s52, s46, s2
	s_addc_u32 s53, s47, 0
	s_add_i32 s64, s64, 1
	s_cmp_lt_u32 s64, 7
	s_barrier
; #define GCOMPUTE(AS, BS) GCOMPUTE_KS(AS, BS, 0) GCOMPUTE_KS(AS, BS, 1)
; template <int EPI>
; DI void gemm_phase(const P& p, int l, const u16* __restrict__ A, const u16* __restrict__ Bt, int mpx, char* lds) {
;     ...
;     __syncthreads();
;     GSTORE(As1, Bs1)
;     {
;       const bool in_tile = kk + 3 < 16;
;       const u16* pa = in_tile ? Ag : Agn;
;       const u16* pb = in_tile ? Bg : Bgn;
;       const int k0 = in_tile ? (kk + 3) * 64 : 0;
;       GLOAD(pa, pb, k0)
;     }
;     __builtin_amdgcn_sched_barrier(0);
;     GCOMPUTE(As0, Bs0)
;     __builtin_amdgcn_sched_barrier(0);
;   }
;   __syncthreads();
;   __builtin_amdgcn_sched_barrier(0);
;   GCOMPUTE(As1, Bs1)
;   __builtin_amdgcn_sched_barrier(0);
	ds_read_b128 v[212:215], v230
	ds_read_b128 v[216:219], v230 offset:2048
	ds_read_b128 v[220:223], v230 offset:4096
	ds_read_b128 v[234:237], v230 offset:6144
	ds_read_b128 v[238:241], v231
	ds_read_b128 v[242:245], v231 offset:2048
	v_mfma_f32_16x16x32_bf16 v[134:137], v[246:249], v[86:89], v[134:137]
	v_mfma_f32_16x16x32_bf16 v[138:141], v[246:249], v[90:93], v[138:141]
	v_mfma_f32_16x16x32_bf16 v[142:145], v[246:249], v[94:97], v[142:145]
	v_mfma_f32_16x16x32_bf16 v[146:149], v[246:249], v[98:101], v[146:149]
	ds_read_b128 v[246:249], v231 offset:4096
	v_mfma_f32_16x16x32_bf16 v[150:153], v[250:253], v[86:89], v[150:153]
	v_mfma_f32_16x16x32_bf16 v[154:157], v[250:253], v[90:93], v[154:157]
	v_mfma_f32_16x16x32_bf16 v[158:161], v[250:253], v[94:97], v[158:161]
	v_mfma_f32_16x16x32_bf16 v[2:5], v[250:253], v[98:101], v[2:5]
	ds_read_b128 v[250:253], v231 offset:6144
	s_cbranch_scc1 .LBB0_70
	s_and_b32 s2, s84, 7
	s_lshl_b32 s2, s2, 8
	s_add_u32 s54, s42, s2
	s_addc_u32 s55, s43, 0
	s_add_u32 s52, s44, s2
	s_addc_u32 s53, s45, 0
	s_waitcnt lgkmcnt(3)
	v_mfma_f32_16x16x32_bf16 v[6:9], v[238:241], v[212:215], v[6:9]
	v_mfma_f32_16x16x32_bf16 v[10:13], v[238:241], v[216:219], v[10:13]
	v_mfma_f32_16x16x32_bf16 v[14:17], v[238:241], v[220:223], v[14:17]
	v_mfma_f32_16x16x32_bf16 v[22:25], v[238:241], v[234:237], v[22:25]
	ds_read_b128 v[238:241], v231 offset:8192
	s_add_i32 m0, s62, 0x20
	s_nop 0
	global_load_lds_dwordx4 v102, s[54:55]
	s_add_i32 m0, s62, 0x2020
	s_nop 0
	global_load_lds_dwordx4 v103, s[54:55]
	s_waitcnt lgkmcnt(3)
	v_mfma_f32_16x16x32_bf16 v[26:29], v[242:245], v[212:215], v[26:29]
	v_mfma_f32_16x16x32_bf16 v[30:33], v[242:245], v[216:219], v[30:33]
	v_mfma_f32_16x16x32_bf16 v[34:37], v[242:245], v[220:223], v[34:37]
	v_mfma_f32_16x16x32_bf16 v[38:41], v[242:245], v[234:237], v[38:41]
	ds_read_b128 v[242:245], v231 offset:10240
	ds_read_b128 v[86:89], v232
	s_add_i32 m0, s62, 0x4020
	s_nop 0
	global_load_lds_dwordx4 v104, s[54:55]
	s_add_i32 m0, s62, 0x6020
	s_nop 0
	global_load_lds_dwordx4 v105, s[54:55]
	s_waitcnt lgkmcnt(4)
	v_mfma_f32_16x16x32_bf16 v[42:45], v[246:249], v[212:215], v[42:45]
	v_mfma_f32_16x16x32_bf16 v[46:49], v[246:249], v[216:219], v[46:49]
	v_mfma_f32_16x16x32_bf16 v[50:53], v[246:249], v[220:223], v[50:53]
	v_mfma_f32_16x16x32_bf16 v[54:57], v[246:249], v[234:237], v[54:57]
	ds_read_b128 v[246:249], v231 offset:12288
	ds_read_b128 v[90:93], v232 offset:2048
	s_add_i32 m0, s62, 0x8020
	s_nop 0
	global_load_lds_dwordx4 v102, s[52:53]
	s_add_i32 m0, s62, 0xa020
	s_nop 0
	global_load_lds_dwordx4 v103, s[52:53]
	s_waitcnt lgkmcnt(5)
	v_mfma_f32_16x16x32_bf16 v[58:61], v[250:253], v[212:215], v[58:61]
	v_mfma_f32_16x16x32_bf16 v[62:65], v[250:253], v[216:219], v[62:65]
	v_mfma_f32_16x16x32_bf16 v[66:69], v[250:253], v[220:223], v[66:69]
	v_mfma_f32_16x16x32_bf16 v[70:73], v[250:253], v[234:237], v[70:73]
	ds_read_b128 v[250:253], v231 offset:14336
	ds_read_b128 v[94:97], v232 offset:4096
	s_add_i32 m0, s62, 0xc020
	s_nop 0
	global_load_lds_dwordx4 v104, s[52:53]
	s_add_i32 m0, s62, 0xe020
	s_nop 0
	global_load_lds_dwordx4 v105, s[52:53]
	s_waitcnt lgkmcnt(6)
	v_mfma_f32_16x16x32_bf16 v[74:77], v[238:241], v[212:215], v[74:77]
	v_mfma_f32_16x16x32_bf16 v[78:81], v[238:241], v[216:219], v[78:81]
	v_mfma_f32_16x16x32_bf16 v[82:85], v[238:241], v[220:223], v[82:85]
	v_mfma_f32_16x16x32_bf16 v[114:117], v[238:241], v[234:237], v[114:117]
	ds_read_b128 v[238:241], v233
	ds_read_b128 v[98:101], v232 offset:6144
	s_waitcnt lgkmcnt(7)
	v_mfma_f32_16x16x32_bf16 v[118:121], v[242:245], v[212:215], v[118:121]
	v_mfma_f32_16x16x32_bf16 v[122:125], v[242:245], v[216:219], v[122:125]
	v_mfma_f32_16x16x32_bf16 v[126:129], v[242:245], v[220:223], v[126:129]
	v_mfma_f32_16x16x32_bf16 v[130:133], v[242:245], v[234:237], v[130:133]
	ds_read_b128 v[242:245], v233 offset:2048
	s_waitcnt lgkmcnt(6)
	v_mfma_f32_16x16x32_bf16 v[134:137], v[246:249], v[212:215], v[134:137]
	v_mfma_f32_16x16x32_bf16 v[138:141], v[246:249], v[216:219], v[138:141]
	v_mfma_f32_16x16x32_bf16 v[142:145], v[246:249], v[220:223], v[142:145]
	v_mfma_f32_16x16x32_bf16 v[146:149], v[246:249], v[234:237], v[146:149]
	ds_read_b128 v[246:249], v233 offset:4096
	s_waitcnt lgkmcnt(5)
	v_mfma_f32_16x16x32_bf16 v[150:153], v[250:253], v[212:215], v[150:153]
	v_mfma_f32_16x16x32_bf16 v[154:157], v[250:253], v[216:219], v[154:157]
	v_mfma_f32_16x16x32_bf16 v[158:161], v[250:253], v[220:223], v[158:161]
	v_mfma_f32_16x16x32_bf16 v[2:5], v[250:253], v[234:237], v[2:5]
	ds_read_b128 v[250:253], v233 offset:6144
	s_waitcnt lgkmcnt(3)
	v_mfma_f32_16x16x32_bf16 v[6:9], v[238:241], v[86:89], v[6:9]
	v_mfma_f32_16x16x32_bf16 v[10:13], v[238:241], v[90:93], v[10:13]
	v_mfma_f32_16x16x32_bf16 v[14:17], v[238:241], v[94:97], v[14:17]
	v_mfma_f32_16x16x32_bf16 v[22:25], v[238:241], v[98:101], v[22:25]
	ds_read_b128 v[238:241], v233 offset:8192
	s_waitcnt lgkmcnt(3)
	v_mfma_f32_16x16x32_bf16 v[26:29], v[242:245], v[86:89], v[26:29]
	v_mfma_f32_16x16x32_bf16 v[30:33], v[242:245], v[90:93], v[30:33]
	v_mfma_f32_16x16x32_bf16 v[34:37], v[242:245], v[94:97], v[34:37]
	v_mfma_f32_16x16x32_bf16 v[38:41], v[242:245], v[98:101], v[38:41]
	ds_read_b128 v[242:245], v233 offset:10240
	s_waitcnt lgkmcnt(3)
	v_mfma_f32_16x16x32_bf16 v[42:45], v[246:249], v[86:89], v[42:45]
	v_mfma_f32_16x16x32_bf16 v[46:49], v[246:249], v[90:93], v[46:49]
	v_mfma_f32_16x16x32_bf16 v[50:53], v[246:249], v[94:97], v[50:53]
	v_mfma_f32_16x16x32_bf16 v[54:57], v[246:249], v[98:101], v[54:57]
	ds_read_b128 v[246:249], v233 offset:12288
	s_waitcnt lgkmcnt(3)
	v_mfma_f32_16x16x32_bf16 v[58:61], v[250:253], v[86:89], v[58:61]
	v_mfma_f32_16x16x32_bf16 v[62:65], v[250:253], v[90:93], v[62:65]
	v_mfma_f32_16x16x32_bf16 v[66:69], v[250:253], v[94:97], v[66:69]
	v_mfma_f32_16x16x32_bf16 v[70:73], v[250:253], v[98:101], v[70:73]
	ds_read_b128 v[250:253], v233 offset:14336
	s_waitcnt lgkmcnt(3)
	v_mfma_f32_16x16x32_bf16 v[74:77], v[238:241], v[86:89], v[74:77]
	v_mfma_f32_16x16x32_bf16 v[78:81], v[238:241], v[90:93], v[78:81]
	v_mfma_f32_16x16x32_bf16 v[82:85], v[238:241], v[94:97], v[82:85]
	v_mfma_f32_16x16x32_bf16 v[114:117], v[238:241], v[98:101], v[114:117]
	s_waitcnt lgkmcnt(2)
	v_mfma_f32_16x16x32_bf16 v[118:121], v[242:245], v[86:89], v[118:121]
	v_mfma_f32_16x16x32_bf16 v[122:125], v[242:245], v[90:93], v[122:125]
	v_mfma_f32_16x16x32_bf16 v[126:129], v[242:245], v[94:97], v[126:129]
	v_mfma_f32_16x16x32_bf16 v[130:133], v[242:245], v[98:101], v[130:133]
	s_waitcnt lgkmcnt(0)
	s_waitcnt vmcnt(0)
	s_barrier
; DI int tidx() { int t = threadIdx.x; asm volatile("" : "+v"(t)); return t; }
; template <int EPI>
; DI void gemm_phase(const P& p, int l, const u16* __restrict__ A, const u16* __restrict__ Bt, int mpx, char* lds) {
;     ...
;   const int tid_e = tidx();
;   const int lane = tid_e & 63, w = tid_e >> 6, r = lane & 15, g = lane >> 4, wm = w >> 2, wn = w & 3;
;   if constexpr (EPI == 1) {
;     const float alpha = 1.4142135623730951f;
;     float* Cw = (float*)(lds + 65536) + w * (16 * 68);
;     const int mr = m0 < MLAT ? (m0 >> 11) : 16;
;     const int colw = n0 + wn * 64;
;     const float* gate = p.mod + (size_t)(l * 17 + mr) * 3072 + 2048 + colw;
;     const float* xr = ((l == 0) ? (m0 < MLAT ? p.x + (size_t)m0 * 1024 : p.ctx + (size_t)(m0 - MLAT) * 1024)
;                                 : p.out + (size_t)m0 * 1024) + (size_t)(wm * 128) * 1024 + colw;
;     float* Z = (float*)p.slab + (size_t)(m0 + wm * 128) * 1024 + colw;
;     const int c4 = (lane & 15) * 4, rr0 = lane >> 4;
;     const float4 gt = *(const float4*)(gate + c4);
;     float4 xn[4];
; #pragma unroll
;     for (int i = 0; i < 4; ++i) xn[i] = *(const float4*)(xr + (size_t)(rr0 + 4 * i) * 1024 + c4);
; #pragma unroll
;     for (int mi = 0; mi < 8; ++mi) {
;       float4 xv[4];
; #pragma unroll
;       for (int i = 0; i < 4; ++i) xv[i] = xn[i];
;       if (mi < 7) {
; #pragma unroll
;         for (int i = 0; i < 4; ++i) xn[i] = *(const float4*)(xr + (size_t)((mi + 1) * 16 + rr0 + 4 * i) * 1024 + c4);
;       }
; #pragma unroll
;       for (int ni = 0; ni < 4; ++ni)
; #pragma unroll
;         for (int j = 0; j < 4; ++j) Cw[(g * 4 + j) * 68 + ni * 16 + r] = acc[mi][ni][j];
;       __builtin_amdgcn_fence(__ATOMIC_RELEASE, "wavefront");
; #pragma unroll
;       for (int i = 0; i < 4; ++i) {
;         const int row = rr0 + 4 * i;
;         const float4 a = *(const float4*)&Cw[row * 68 + c4];
;         float4 z;
;         z.x = alpha * xv[i].x + gt.x * a.x;
;         z.y = alpha * xv[i].y + gt.y * a.y;
;         z.z = alpha * xv[i].z + gt.z * a.z;
;         z.w = alpha * xv[i].w + gt.w * a.w;
;         *(float4*)(Z + (size_t)(mi * 16 + row) * 1024 + c4) = z;
;       }
	v_mfma_f32_16x16x32_bf16 v[134:137], v[246:249], v[86:89], v[134:137]
	v_mfma_f32_16x16x32_bf16 v[138:141], v[246:249], v[90:93], v[138:141]
	v_mfma_f32_16x16x32_bf16 v[142:145], v[246:249], v[94:97], v[142:145]
	v_mfma_f32_16x16x32_bf16 v[146:149], v[246:249], v[98:101], v[146:149]
	v_mfma_f32_16x16x32_bf16 v[150:153], v[250:253], v[86:89], v[150:153]
	v_mfma_f32_16x16x32_bf16 v[154:157], v[250:253], v[90:93], v[154:157]
	v_mfma_f32_16x16x32_bf16 v[158:161], v[250:253], v[94:97], v[158:161]
	v_mfma_f32_16x16x32_bf16 v[2:5], v[250:253], v[98:101], v[2:5]
	s_nop 0
	v_readfirstlane_b32 s62, v195
	s_lshr_b32 s62, s62, 6
	s_and_b32 s63, s62, 3
	s_lshr_b32 s68, s62, 2
	s_lshl_b32 s63, s63, 6
	s_add_i32 s63, s63, s61
	s_lshl_b32 s68, s68, 7
	s_add_i32 s68, s68, s60
	s_min_u32 s2, s60, 0x8000
	s_lshr_b32 s2, s2, 11
	s_mul_i32 s69, s50, 17
	s_add_i32 s2, s2, s69
	s_mul_i32 s2, s2, 0x3000
	s_lshl_b32 s69, s63, 2
	s_add_i32 s2, s2, s69
	s_addk_i32 s2, 0x2000
	v_readlane_b32 s70, v255, 30
	v_readlane_b32 s71, v255, 31
	s_add_u32 s70, s70, s2
	s_addc_u32 s71, s71, 0
	v_and_b32_e32 v249, 15, v226
	v_lshrrev_b32_e32 v250, 4, v226
	v_lshlrev_b32_e32 v251, 4, v249
	global_load_dwordx4 v[212:215], v251, s[70:71]
	v_lshl_add_u32 v248, v250, 12, v251
	s_cmp_lt_u32 s60, 0x8000
	s_cselect_b32 s2, 0, 16
	s_cselect_b32 s69, 0, 0x8000
	s_cmp_eq_u32 s50, 0
	s_cselect_b32 s2, s2, 0x88
	s_cselect_b32 s69, s69, 0
	s_add_u32 s70, s96, s2
	s_addc_u32 s71, s97, 0
	s_load_dwordx2 s[64:65], s[70:71], 0x0
	s_sub_i32 s69, s68, s69
	s_mov_b32 s70, s69
	s_mov_b32 s71, 0
	s_lshl_b64 s[70:71], s[70:71], 12
	s_lshl_b32 s2, s63, 2
	s_add_u32 s70, s70, s2
	s_addc_u32 s71, s71, 0
	s_waitcnt lgkmcnt(0)
	s_add_u32 s64, s64, s70
	s_addc_u32 s65, s65, s71
	s_mov_b32 s70, s68
	s_mov_b32 s71, 0
	s_lshl_b64 s[70:71], s[70:71], 12
	s_add_u32 s70, s70, s2
	s_addc_u32 s71, s71, 0
	s_add_u32 s66, s18, s70
	s_addc_u32 s67, s19, s71
	s_mul_i32 s2, s62, 0x1100
	s_add_i32 s2, s2, s78
	v_mul_u32_u24_e32 v246, 0x440, v250
	v_lshl_add_u32 v246, v249, 2, v246
	v_add_u32_e32 v246, s2, v246
	v_mul_u32_u24_e32 v247, 0x110, v250
	v_add_u32_e32 v247, v247, v251
	v_add_u32_e32 v247, s2, v247
	global_load_dwordx4 v[18:21], v248, s[64:65]
	s_add_u32 s64, s64, 0x4000
	s_addc_u32 s65, s65, 0
	global_load_dwordx4 v[86:89], v248, s[64:65]
	s_add_u32 s64, s64, 0x4000
	s_addc_u32 s65, s65, 0
	global_load_dwordx4 v[90:93], v248, s[64:65]
	s_add_u32 s64, s64, 0x4000
	s_addc_u32 s65, s65, 0
	global_load_dwordx4 v[94:97], v248, s[64:65]
	s_add_u32 s64, s64, 0x4000
	s_addc_u32 s65, s65, 0
	global_load_dwordx4 v[98:101], v248, s[64:65]
	s_add_u32 s64, s64, 0x4000
	s_addc_u32 s65, s65, 0
	global_load_dwordx4 v[102:105], v248, s[64:65]
	s_add_u32 s64, s64, 0x4000
	s_addc_u32 s65, s65, 0
	global_load_dwordx4 v[106:109], v248, s[64:65]
	s_add_u32 s64, s64, 0x4000
	s_addc_u32 s65, s65, 0
	global_load_dwordx4 v[110:113], v248, s[64:65]
	s_add_u32 s64, s64, 0x4000
	s_addc_u32 s65, s65, 0
	global_load_dwordx4 v[162:165], v248, s[64:65]
	s_add_u32 s64, s64, 0x4000
	s_addc_u32 s65, s65, 0
	global_load_dwordx4 v[166:169], v248, s[64:65]
	s_add_u32 s64, s64, 0x4000
	s_addc_u32 s65, s65, 0
	global_load_dwordx4 v[170:173], v248, s[64:65]
	s_add_u32 s64, s64, 0x4000
	s_addc_u32 s65, s65, 0
	global_load_dwordx4 v[174:177], v248, s[64:65]
	s_add_u32 s64, s64, 0x4000
	s_addc_u32 s65, s65, 0
	global_load_dwordx4 v[178:181], v248, s[64:65]
	s_add_u32 s64, s64, 0x4000
	s_addc_u32 s65, s65, 0
	global_load_dwordx4 v[182:185], v248, s[64:65]
	s_add_u32 s64, s64, 0x4000
	s_addc_u32 s65, s65, 0
	global_load_dwordx4 v[186:189], v248, s[64:65]
	s_add_u32 s64, s64, 0x4000
	s_addc_u32 s65, s65, 0
	global_load_dwordx4 v[190:193], v248, s[64:65]
	s_add_u32 s64, s64, 0x4000
	s_addc_u32 s65, s65, 0
	ds_write2_b32 v246, v6, v10 offset0:0 offset1:16
	ds_write2_b32 v246, v14, v22 offset0:32 offset1:48
	ds_write2_b32 v246, v7, v11 offset0:68 offset1:84
	ds_write2_b32 v246, v15, v23 offset0:100 offset1:116
	ds_write2_b32 v246, v8, v12 offset0:136 offset1:152
	ds_write2_b32 v246, v16, v24 offset0:168 offset1:184
	ds_write2_b32 v246, v9, v13 offset0:204 offset1:220
	ds_write2_b32 v246, v17, v25 offset0:236 offset1:252
	ds_read_b128 v[216:219], v247 offset:0
	ds_read_b128 v[220:223], v247 offset:1088
	ds_read_b128 v[238:241], v247 offset:2176
	ds_read_b128 v[242:245], v247 offset:3264
	s_waitcnt vmcnt(12)
	s_waitcnt lgkmcnt(3)
	v_mul_f32_e32 v216, v212, v216
	v_mul_f32_e32 v217, v213, v217
	v_mul_f32_e32 v218, v214, v218
	v_mul_f32_e32 v219, v215, v219
	v_fma_f32 v18, v18, s34, v216
	v_fma_f32 v19, v19, s34, v217
	v_fma_f32 v20, v20, s34, v218
	v_fma_f32 v21, v21, s34, v219
	s_waitcnt lgkmcnt(2)
	v_mul_f32_e32 v220, v212, v220
	v_mul_f32_e32 v221, v213, v221
	v_mul_f32_e32 v222, v214, v222
	v_mul_f32_e32 v223, v215, v223
	v_fma_f32 v86, v86, s34, v220
	v_fma_f32 v87, v87, s34, v221
	v_fma_f32 v88, v88, s34, v222
	v_fma_f32 v89, v89, s34, v223
	s_waitcnt lgkmcnt(1)
	v_mul_f32_e32 v238, v212, v238
	v_mul_f32_e32 v239, v213, v239
	v_mul_f32_e32 v240, v214, v240
	v_mul_f32_e32 v241, v215, v241
	v_fma_f32 v90, v90, s34, v238
	v_fma_f32 v91, v91, s34, v239
	v_fma_f32 v92, v92, s34, v240
	v_fma_f32 v93, v93, s34, v241
	s_waitcnt lgkmcnt(0)
; template <int EPI>
; DI void gemm_phase(const P& p, int l, const u16* __restrict__ A, const u16* __restrict__ Bt, int mpx, char* lds) {
;     ...
;     const int c4 = (lane & 15) * 4, rr0 = lane >> 4;
;     const float4 gt = *(const float4*)(gate + c4);
;     float4 xn[4];
; #pragma unroll
;     for (int i = 0; i < 4; ++i) xn[i] = *(const float4*)(xr + (size_t)(rr0 + 4 * i) * 1024 + c4);
; #pragma unroll
;     for (int mi = 0; mi < 8; ++mi) {
;       float4 xv[4];
; #pragma unroll
;       for (int i = 0; i < 4; ++i) xv[i] = xn[i];
;       if (mi < 7) {
; #pragma unroll
;         for (int i = 0; i < 4; ++i) xn[i] = *(const float4*)(xr + (size_t)((mi + 1) * 16 + rr0 + 4 * i) * 1024 + c4);
;       }
; #pragma unroll
;       for (int ni = 0; ni < 4; ++ni)
; #pragma unroll
;         for (int j = 0; j < 4; ++j) Cw[(g * 4 + j) * 68 + ni * 16 + r] = acc[mi][ni][j];
;       __builtin_amdgcn_fence(__ATOMIC_RELEASE, "wavefront");
; #pragma unroll
;       for (int i = 0; i < 4; ++i) {
;         const int row = rr0 + 4 * i;
;         const float4 a = *(const float4*)&Cw[row * 68 + c4];
;         float4 z;
;         z.x = alpha * xv[i].x + gt.x * a.x;
;         z.y = alpha * xv[i].y + gt.y * a.y;
;         z.z = alpha * xv[i].z + gt.z * a.z;
;         z.w = alpha * xv[i].w + gt.w * a.w;
;         *(float4*)(Z + (size_t)(mi * 16 + row) * 1024 + c4) = z;
;       }
;       __builtin_amdgcn_fence(__ATOMIC_RELEASE, "wavefront");
	v_mul_f32_e32 v242, v212, v242
	v_mul_f32_e32 v243, v213, v243
	v_mul_f32_e32 v244, v214, v244
	v_mul_f32_e32 v245, v215, v245
	v_fma_f32 v94, v94, s34, v242
	v_fma_f32 v95, v95, s34, v243
	v_fma_f32 v96, v96, s34, v244
	v_fma_f32 v97, v97, s34, v245
	ds_write2_b32 v246, v26, v30 offset0:0 offset1:16
	ds_write2_b32 v246, v34, v38 offset0:32 offset1:48
	ds_write2_b32 v246, v27, v31 offset0:68 offset1:84
	ds_write2_b32 v246, v35, v39 offset0:100 offset1:116
	ds_write2_b32 v246, v28, v32 offset0:136 offset1:152
	ds_write2_b32 v246, v36, v40 offset0:168 offset1:184
	ds_write2_b32 v246, v29, v33 offset0:204 offset1:220
	ds_write2_b32 v246, v37, v41 offset0:236 offset1:252
	ds_read_b128 v[216:219], v247 offset:0
	ds_read_b128 v[220:223], v247 offset:1088
	ds_read_b128 v[238:241], v247 offset:2176
	ds_read_b128 v[242:245], v247 offset:3264
	s_waitcnt vmcnt(8)
	s_waitcnt lgkmcnt(3)
	v_mul_f32_e32 v216, v212, v216
	v_mul_f32_e32 v217, v213, v217
	v_mul_f32_e32 v218, v214, v218
	v_mul_f32_e32 v219, v215, v219
	v_fma_f32 v98, v98, s34, v216
	v_fma_f32 v99, v99, s34, v217
	v_fma_f32 v100, v100, s34, v218
	v_fma_f32 v101, v101, s34, v219
	s_waitcnt lgkmcnt(2)
	v_mul_f32_e32 v220, v212, v220
	v_mul_f32_e32 v221, v213, v221
	v_mul_f32_e32 v222, v214, v222
	v_mul_f32_e32 v223, v215, v223
	v_fma_f32 v102, v102, s34, v220
	v_fma_f32 v103, v103, s34, v221
	v_fma_f32 v104, v104, s34, v222
	v_fma_f32 v105, v105, s34, v223
	s_waitcnt lgkmcnt(1)
	v_mul_f32_e32 v238, v212, v238
	v_mul_f32_e32 v239, v213, v239
	v_mul_f32_e32 v240, v214, v240
	v_mul_f32_e32 v241, v215, v241
	v_fma_f32 v106, v106, s34, v238
	v_fma_f32 v107, v107, s34, v239
	v_fma_f32 v108, v108, s34, v240
	v_fma_f32 v109, v109, s34, v241
	s_waitcnt lgkmcnt(0)
	v_mul_f32_e32 v242, v212, v242
	v_mul_f32_e32 v243, v213, v243
	v_mul_f32_e32 v244, v214, v244
	v_mul_f32_e32 v245, v215, v245
	v_fma_f32 v110, v110, s34, v242
	v_fma_f32 v111, v111, s34, v243
	v_fma_f32 v112, v112, s34, v244
	v_fma_f32 v113, v113, s34, v245
	ds_write2_b32 v246, v42, v46 offset0:0 offset1:16
	ds_write2_b32 v246, v50, v54 offset0:32 offset1:48
	ds_write2_b32 v246, v43, v47 offset0:68 offset1:84
	ds_write2_b32 v246, v51, v55 offset0:100 offset1:116
	ds_write2_b32 v246, v44, v48 offset0:136 offset1:152
	ds_write2_b32 v246, v52, v56 offset0:168 offset1:184
	ds_write2_b32 v246, v45, v49 offset0:204 offset1:220
	ds_write2_b32 v246, v53, v57 offset0:236 offset1:252
	ds_read_b128 v[216:219], v247 offset:0
	ds_read_b128 v[220:223], v247 offset:1088
	ds_read_b128 v[238:241], v247 offset:2176
	ds_read_b128 v[242:245], v247 offset:3264
	s_waitcnt vmcnt(4)
	s_waitcnt lgkmcnt(3)
	v_mul_f32_e32 v216, v212, v216
	v_mul_f32_e32 v217, v213, v217
	v_mul_f32_e32 v218, v214, v218
	v_mul_f32_e32 v219, v215, v219
	v_fma_f32 v162, v162, s34, v216
	v_fma_f32 v163, v163, s34, v217
	v_fma_f32 v164, v164, s34, v218
	v_fma_f32 v165, v165, s34, v219
	s_waitcnt lgkmcnt(2)
	v_mul_f32_e32 v220, v212, v220
	v_mul_f32_e32 v221, v213, v221
	v_mul_f32_e32 v222, v214, v222
	v_mul_f32_e32 v223, v215, v223
	v_fma_f32 v166, v166, s34, v220
	v_fma_f32 v167, v167, s34, v221
	v_fma_f32 v168, v168, s34, v222
	v_fma_f32 v169, v169, s34, v223
	s_waitcnt lgkmcnt(1)
	v_mul_f32_e32 v238, v212, v238
	v_mul_f32_e32 v239, v213, v239
	v_mul_f32_e32 v240, v214, v240
	v_mul_f32_e32 v241, v215, v241
	v_fma_f32 v170, v170, s34, v238
	v_fma_f32 v171, v171, s34, v239
	v_fma_f32 v172, v172, s34, v240
	v_fma_f32 v173, v173, s34, v241
	s_waitcnt lgkmcnt(0)
	v_mul_f32_e32 v242, v212, v242
	v_mul_f32_e32 v243, v213, v243
	v_mul_f32_e32 v244, v214, v244
	v_mul_f32_e32 v245, v215, v245
	v_fma_f32 v174, v174, s34, v242
	v_fma_f32 v175, v175, s34, v243
	v_fma_f32 v176, v176, s34, v244
	v_fma_f32 v177, v177, s34, v245
	ds_write2_b32 v246, v58, v62 offset0:0 offset1:16
	ds_write2_b32 v246, v66, v70 offset0:32 offset1:48
	ds_write2_b32 v246, v59, v63 offset0:68 offset1:84
	ds_write2_b32 v246, v67, v71 offset0:100 offset1:116
	ds_write2_b32 v246, v60, v64 offset0:136 offset1:152
	ds_write2_b32 v246, v68, v72 offset0:168 offset1:184
	ds_write2_b32 v246, v61, v65 offset0:204 offset1:220
	ds_write2_b32 v246, v69, v73 offset0:236 offset1:252
	ds_read_b128 v[216:219], v247 offset:0
	ds_read_b128 v[220:223], v247 offset:1088
	ds_read_b128 v[238:241], v247 offset:2176
	ds_read_b128 v[242:245], v247 offset:3264
	s_waitcnt vmcnt(0)
	s_waitcnt lgkmcnt(3)
	v_mul_f32_e32 v216, v212, v216
	v_mul_f32_e32 v217, v213, v217
	v_mul_f32_e32 v218, v214, v218
	v_mul_f32_e32 v219, v215, v219
	v_fma_f32 v178, v178, s34, v216
	v_fma_f32 v179, v179, s34, v217
	v_fma_f32 v180, v180, s34, v218
	v_fma_f32 v181, v181, s34, v219
	s_waitcnt lgkmcnt(2)
	v_mul_f32_e32 v220, v212, v220
	v_mul_f32_e32 v221, v213, v221
	v_mul_f32_e32 v222, v214, v222
	v_mul_f32_e32 v223, v215, v223
	v_fma_f32 v182, v182, s34, v220
	v_fma_f32 v183, v183, s34, v221
	v_fma_f32 v184, v184, s34, v222
	v_fma_f32 v185, v185, s34, v223
	s_waitcnt lgkmcnt(1)
	v_mul_f32_e32 v238, v212, v238
	v_mul_f32_e32 v239, v213, v239
	v_mul_f32_e32 v240, v214, v240
	v_mul_f32_e32 v241, v215, v241
	v_fma_f32 v186, v186, s34, v238
	v_fma_f32 v187, v187, s34, v239
	v_fma_f32 v188, v188, s34, v240
	v_fma_f32 v189, v189, s34, v241
	s_waitcnt lgkmcnt(0)
; template <int EPI>
; DI void gemm_phase(const P& p, int l, const u16* __restrict__ A, const u16* __restrict__ Bt, int mpx, char* lds) {
;     ...
;     for (int mi = 0; mi < 8; ++mi) {
;       float4 xv[4];
; #pragma unroll
;       for (int i = 0; i < 4; ++i) xv[i] = xn[i];
;       if (mi < 7) {
; #pragma unroll
;         for (int i = 0; i < 4; ++i) xn[i] = *(const float4*)(xr + (size_t)((mi + 1) * 16 + rr0 + 4 * i) * 1024 + c4);
;       }
; #pragma unroll
;       for (int ni = 0; ni < 4; ++ni)
; #pragma unroll
;         for (int j = 0; j < 4; ++j) Cw[(g * 4 + j) * 68 + ni * 16 + r] = acc[mi][ni][j];
;       __builtin_amdgcn_fence(__ATOMIC_RELEASE, "wavefront");
; #pragma unroll
;       for (int i = 0; i < 4; ++i) {
;         const int row = rr0 + 4 * i;
;         const float4 a = *(const float4*)&Cw[row * 68 + c4];
;         float4 z;
;         z.x = alpha * xv[i].x + gt.x * a.x;
;         z.y = alpha * xv[i].y + gt.y * a.y;
;         z.z = alpha * xv[i].z + gt.z * a.z;
;         z.w = alpha * xv[i].w + gt.w * a.w;
;         *(float4*)(Z + (size_t)(mi * 16 + row) * 1024 + c4) = z;
;       }
;       __builtin_amdgcn_fence(__ATOMIC_RELEASE, "wavefront");
	v_mul_f32_e32 v242, v212, v242
	v_mul_f32_e32 v243, v213, v243
	v_mul_f32_e32 v244, v214, v244
	v_mul_f32_e32 v245, v215, v245
	v_fma_f32 v190, v190, s34, v242
	v_fma_f32 v191, v191, s34, v243
	v_fma_f32 v192, v192, s34, v244
	v_fma_f32 v193, v193, s34, v245
	global_load_dwordx4 v[6:9], v248, s[64:65]
	s_add_u32 s64, s64, 0x4000
	s_addc_u32 s65, s65, 0
	global_load_dwordx4 v[10:13], v248, s[64:65]
	s_add_u32 s64, s64, 0x4000
	s_addc_u32 s65, s65, 0
	global_load_dwordx4 v[14:17], v248, s[64:65]
	s_add_u32 s64, s64, 0x4000
	s_addc_u32 s65, s65, 0
	global_load_dwordx4 v[22:25], v248, s[64:65]
	s_add_u32 s64, s64, 0x4000
	s_addc_u32 s65, s65, 0
	global_load_dwordx4 v[26:29], v248, s[64:65]
	s_add_u32 s64, s64, 0x4000
	s_addc_u32 s65, s65, 0
	global_load_dwordx4 v[30:33], v248, s[64:65]
	s_add_u32 s64, s64, 0x4000
	s_addc_u32 s65, s65, 0
	global_load_dwordx4 v[34:37], v248, s[64:65]
	s_add_u32 s64, s64, 0x4000
	s_addc_u32 s65, s65, 0
	global_load_dwordx4 v[38:41], v248, s[64:65]
	s_add_u32 s64, s64, 0x4000
	s_addc_u32 s65, s65, 0
	global_load_dwordx4 v[42:45], v248, s[64:65]
	s_add_u32 s64, s64, 0x4000
	s_addc_u32 s65, s65, 0
	global_load_dwordx4 v[46:49], v248, s[64:65]
	s_add_u32 s64, s64, 0x4000
	s_addc_u32 s65, s65, 0
	global_load_dwordx4 v[50:53], v248, s[64:65]
	s_add_u32 s64, s64, 0x4000
	s_addc_u32 s65, s65, 0
	global_load_dwordx4 v[54:57], v248, s[64:65]
	s_add_u32 s64, s64, 0x4000
	s_addc_u32 s65, s65, 0
	global_load_dwordx4 v[58:61], v248, s[64:65]
	s_add_u32 s64, s64, 0x4000
	s_addc_u32 s65, s65, 0
	global_load_dwordx4 v[62:65], v248, s[64:65]
	s_add_u32 s64, s64, 0x4000
	s_addc_u32 s65, s65, 0
	global_load_dwordx4 v[66:69], v248, s[64:65]
	s_add_u32 s64, s64, 0x4000
	s_addc_u32 s65, s65, 0
	global_load_dwordx4 v[70:73], v248, s[64:65]
	s_add_u32 s64, s64, 0x4000
	s_addc_u32 s65, s65, 0
	global_store_dwordx4 v248, v[18:21], s[66:67] sc1
	s_add_u32 s66, s66, 0x4000
	s_addc_u32 s67, s67, 0
	global_store_dwordx4 v248, v[86:89], s[66:67] sc1
	s_add_u32 s66, s66, 0x4000
	s_addc_u32 s67, s67, 0
	global_store_dwordx4 v248, v[90:93], s[66:67] sc1
	s_add_u32 s66, s66, 0x4000
	s_addc_u32 s67, s67, 0
	global_store_dwordx4 v248, v[94:97], s[66:67] sc1
	s_add_u32 s66, s66, 0x4000
	s_addc_u32 s67, s67, 0
	global_store_dwordx4 v248, v[98:101], s[66:67] sc1
	s_add_u32 s66, s66, 0x4000
	s_addc_u32 s67, s67, 0
	global_store_dwordx4 v248, v[102:105], s[66:67] sc1
	s_add_u32 s66, s66, 0x4000
	s_addc_u32 s67, s67, 0
	global_store_dwordx4 v248, v[106:109], s[66:67] sc1
	s_add_u32 s66, s66, 0x4000
	s_addc_u32 s67, s67, 0
	global_store_dwordx4 v248, v[110:113], s[66:67] sc1
	s_add_u32 s66, s66, 0x4000
	s_addc_u32 s67, s67, 0
	global_store_dwordx4 v248, v[162:165], s[66:67] sc1
	s_add_u32 s66, s66, 0x4000
	s_addc_u32 s67, s67, 0
	global_store_dwordx4 v248, v[166:169], s[66:67] sc1
	s_add_u32 s66, s66, 0x4000
	s_addc_u32 s67, s67, 0
	global_store_dwordx4 v248, v[170:173], s[66:67] sc1
	s_add_u32 s66, s66, 0x4000
	s_addc_u32 s67, s67, 0
	global_store_dwordx4 v248, v[174:177], s[66:67] sc1
	s_add_u32 s66, s66, 0x4000
	s_addc_u32 s67, s67, 0
	global_store_dwordx4 v248, v[178:181], s[66:67] sc1
	s_add_u32 s66, s66, 0x4000
	s_addc_u32 s67, s67, 0
	global_store_dwordx4 v248, v[182:185], s[66:67] sc1
	s_add_u32 s66, s66, 0x4000
	s_addc_u32 s67, s67, 0
	global_store_dwordx4 v248, v[186:189], s[66:67] sc1
	s_add_u32 s66, s66, 0x4000
	s_addc_u32 s67, s67, 0
	global_store_dwordx4 v248, v[190:193], s[66:67] sc1
	s_add_u32 s66, s66, 0x4000
	s_addc_u32 s67, s67, 0
	ds_write2_b32 v246, v74, v78 offset0:0 offset1:16
	ds_write2_b32 v246, v82, v114 offset0:32 offset1:48
	ds_write2_b32 v246, v75, v79 offset0:68 offset1:84
	ds_write2_b32 v246, v83, v115 offset0:100 offset1:116
	ds_write2_b32 v246, v76, v80 offset0:136 offset1:152
	ds_write2_b32 v246, v84, v116 offset0:168 offset1:184
	ds_write2_b32 v246, v77, v81 offset0:204 offset1:220
	ds_write2_b32 v246, v85, v117 offset0:236 offset1:252
	ds_read_b128 v[216:219], v247 offset:0
	ds_read_b128 v[220:223], v247 offset:1088
	ds_read_b128 v[238:241], v247 offset:2176
	ds_read_b128 v[242:245], v247 offset:3264
	s_waitcnt vmcnt(28)
	s_waitcnt lgkmcnt(3)
	v_mul_f32_e32 v216, v212, v216
	v_mul_f32_e32 v217, v213, v217
	v_mul_f32_e32 v218, v214, v218
	v_mul_f32_e32 v219, v215, v219
	v_fma_f32 v6, v6, s34, v216
	v_fma_f32 v7, v7, s34, v217
	v_fma_f32 v8, v8, s34, v218
	v_fma_f32 v9, v9, s34, v219
	s_waitcnt lgkmcnt(2)
	v_mul_f32_e32 v220, v212, v220
	v_mul_f32_e32 v221, v213, v221
	v_mul_f32_e32 v222, v214, v222
	v_mul_f32_e32 v223, v215, v223
	v_fma_f32 v10, v10, s34, v220
	v_fma_f32 v11, v11, s34, v221
	v_fma_f32 v12, v12, s34, v222
	v_fma_f32 v13, v13, s34, v223
	s_waitcnt lgkmcnt(1)
	v_mul_f32_e32 v238, v212, v238
	v_mul_f32_e32 v239, v213, v239
	v_mul_f32_e32 v240, v214, v240
	v_mul_f32_e32 v241, v215, v241
	v_fma_f32 v14, v14, s34, v238
	v_fma_f32 v15, v15, s34, v239
	v_fma_f32 v16, v16, s34, v240
	v_fma_f32 v17, v17, s34, v241
	s_waitcnt lgkmcnt(0)
	v_mul_f32_e32 v242, v212, v242
	v_mul_f32_e32 v243, v213, v243
	v_mul_f32_e32 v244, v214, v244
	v_mul_f32_e32 v245, v215, v245
	v_fma_f32 v22, v22, s34, v242
	v_fma_f32 v23, v23, s34, v243
	v_fma_f32 v24, v24, s34, v244
	v_fma_f32 v25, v25, s34, v245
	ds_write2_b32 v246, v118, v122 offset0:0 offset1:16
	ds_write2_b32 v246, v126, v130 offset0:32 offset1:48
	ds_write2_b32 v246, v119, v123 offset0:68 offset1:84
	ds_write2_b32 v246, v127, v131 offset0:100 offset1:116
	ds_write2_b32 v246, v120, v124 offset0:136 offset1:152
	ds_write2_b32 v246, v128, v132 offset0:168 offset1:184
	ds_write2_b32 v246, v121, v125 offset0:204 offset1:220
	ds_write2_b32 v246, v129, v133 offset0:236 offset1:252
	ds_read_b128 v[216:219], v247 offset:0
	ds_read_b128 v[220:223], v247 offset:1088
	ds_read_b128 v[238:241], v247 offset:2176
	ds_read_b128 v[242:245], v247 offset:3264
	s_waitcnt vmcnt(24)
; template <int EPI>
; DI void gemm_phase(const P& p, int l, const u16* __restrict__ A, const u16* __restrict__ Bt, int mpx, char* lds) {
;     ...
;     for (int mi = 0; mi < 8; ++mi) {
;       float4 xv[4];
; #pragma unroll
;       for (int i = 0; i < 4; ++i) xv[i] = xn[i];
;       if (mi < 7) {
; #pragma unroll
;         for (int i = 0; i < 4; ++i) xn[i] = *(const float4*)(xr + (size_t)((mi + 1) * 16 + rr0 + 4 * i) * 1024 + c4);
;       }
; #pragma unroll
;       for (int ni = 0; ni < 4; ++ni)
; #pragma unroll
;         for (int j = 0; j < 4; ++j) Cw[(g * 4 + j) * 68 + ni * 16 + r] = acc[mi][ni][j];
;       __builtin_amdgcn_fence(__ATOMIC_RELEASE, "wavefront");
; #pragma unroll
;       for (int i = 0; i < 4; ++i) {
;         const int row = rr0 + 4 * i;
;         const float4 a = *(const float4*)&Cw[row * 68 + c4];
;         float4 z;
;         z.x = alpha * xv[i].x + gt.x * a.x;
;         z.y = alpha * xv[i].y + gt.y * a.y;
;         z.z = alpha * xv[i].z + gt.z * a.z;
;         z.w = alpha * xv[i].w + gt.w * a.w;
;         *(float4*)(Z + (size_t)(mi * 16 + row) * 1024 + c4) = z;
;       }
;       __builtin_amdgcn_fence(__ATOMIC_RELEASE, "wavefront");
;     ...
;   if (!has_next) break;
;   t = tn; m0 = m1; n0 = n1; Ag = Agn; Bg = Bgn;
	s_waitcnt lgkmcnt(3)
	v_mul_f32_e32 v216, v212, v216
	v_mul_f32_e32 v217, v213, v217
	v_mul_f32_e32 v218, v214, v218
	v_mul_f32_e32 v219, v215, v219
	v_fma_f32 v26, v26, s34, v216
	v_fma_f32 v27, v27, s34, v217
	v_fma_f32 v28, v28, s34, v218
	v_fma_f32 v29, v29, s34, v219
	s_waitcnt lgkmcnt(2)
	v_mul_f32_e32 v220, v212, v220
	v_mul_f32_e32 v221, v213, v221
	v_mul_f32_e32 v222, v214, v222
	v_mul_f32_e32 v223, v215, v223
	v_fma_f32 v30, v30, s34, v220
	v_fma_f32 v31, v31, s34, v221
	v_fma_f32 v32, v32, s34, v222
	v_fma_f32 v33, v33, s34, v223
	s_waitcnt lgkmcnt(1)
	v_mul_f32_e32 v238, v212, v238
	v_mul_f32_e32 v239, v213, v239
	v_mul_f32_e32 v240, v214, v240
	v_mul_f32_e32 v241, v215, v241
	v_fma_f32 v34, v34, s34, v238
	v_fma_f32 v35, v35, s34, v239
	v_fma_f32 v36, v36, s34, v240
	v_fma_f32 v37, v37, s34, v241
	s_waitcnt lgkmcnt(0)
	v_mul_f32_e32 v242, v212, v242
	v_mul_f32_e32 v243, v213, v243
	v_mul_f32_e32 v244, v214, v244
	v_mul_f32_e32 v245, v215, v245
	v_fma_f32 v38, v38, s34, v242
	v_fma_f32 v39, v39, s34, v243
	v_fma_f32 v40, v40, s34, v244
	v_fma_f32 v41, v41, s34, v245
	ds_write2_b32 v246, v134, v138 offset0:0 offset1:16
	ds_write2_b32 v246, v142, v146 offset0:32 offset1:48
	ds_write2_b32 v246, v135, v139 offset0:68 offset1:84
	ds_write2_b32 v246, v143, v147 offset0:100 offset1:116
	ds_write2_b32 v246, v136, v140 offset0:136 offset1:152
	ds_write2_b32 v246, v144, v148 offset0:168 offset1:184
	ds_write2_b32 v246, v137, v141 offset0:204 offset1:220
	ds_write2_b32 v246, v145, v149 offset0:236 offset1:252
	ds_read_b128 v[216:219], v247 offset:0
	ds_read_b128 v[220:223], v247 offset:1088
	ds_read_b128 v[238:241], v247 offset:2176
	ds_read_b128 v[242:245], v247 offset:3264
	s_waitcnt vmcnt(20)
	s_waitcnt lgkmcnt(3)
	v_mul_f32_e32 v216, v212, v216
	v_mul_f32_e32 v217, v213, v217
	v_mul_f32_e32 v218, v214, v218
	v_mul_f32_e32 v219, v215, v219
	v_fma_f32 v42, v42, s34, v216
	v_fma_f32 v43, v43, s34, v217
	v_fma_f32 v44, v44, s34, v218
	v_fma_f32 v45, v45, s34, v219
	s_waitcnt lgkmcnt(2)
	v_mul_f32_e32 v220, v212, v220
	v_mul_f32_e32 v221, v213, v221
	v_mul_f32_e32 v222, v214, v222
	v_mul_f32_e32 v223, v215, v223
	v_fma_f32 v46, v46, s34, v220
	v_fma_f32 v47, v47, s34, v221
	v_fma_f32 v48, v48, s34, v222
	v_fma_f32 v49, v49, s34, v223
	s_waitcnt lgkmcnt(1)
	v_mul_f32_e32 v238, v212, v238
	v_mul_f32_e32 v239, v213, v239
	v_mul_f32_e32 v240, v214, v240
	v_mul_f32_e32 v241, v215, v241
	v_fma_f32 v50, v50, s34, v238
	v_fma_f32 v51, v51, s34, v239
	v_fma_f32 v52, v52, s34, v240
	v_fma_f32 v53, v53, s34, v241
	s_waitcnt lgkmcnt(0)
	v_mul_f32_e32 v242, v212, v242
	v_mul_f32_e32 v243, v213, v243
	v_mul_f32_e32 v244, v214, v244
	v_mul_f32_e32 v245, v215, v245
	v_fma_f32 v54, v54, s34, v242
	v_fma_f32 v55, v55, s34, v243
	v_fma_f32 v56, v56, s34, v244
	v_fma_f32 v57, v57, s34, v245
	ds_write2_b32 v246, v150, v154 offset0:0 offset1:16
	ds_write2_b32 v246, v158, v2 offset0:32 offset1:48
	ds_write2_b32 v246, v151, v155 offset0:68 offset1:84
	ds_write2_b32 v246, v159, v3 offset0:100 offset1:116
	ds_write2_b32 v246, v152, v156 offset0:136 offset1:152
	ds_write2_b32 v246, v160, v4 offset0:168 offset1:184
	ds_write2_b32 v246, v153, v157 offset0:204 offset1:220
	ds_write2_b32 v246, v161, v5 offset0:236 offset1:252
	ds_read_b128 v[216:219], v247 offset:0
	ds_read_b128 v[220:223], v247 offset:1088
	ds_read_b128 v[238:241], v247 offset:2176
	ds_read_b128 v[242:245], v247 offset:3264
	s_waitcnt vmcnt(16)
	s_waitcnt lgkmcnt(3)
	v_mul_f32_e32 v216, v212, v216
	v_mul_f32_e32 v217, v213, v217
	v_mul_f32_e32 v218, v214, v218
	v_mul_f32_e32 v219, v215, v219
	v_fma_f32 v58, v58, s34, v216
	v_fma_f32 v59, v59, s34, v217
	v_fma_f32 v60, v60, s34, v218
	v_fma_f32 v61, v61, s34, v219
	s_waitcnt lgkmcnt(2)
	v_mul_f32_e32 v220, v212, v220
	v_mul_f32_e32 v221, v213, v221
	v_mul_f32_e32 v222, v214, v222
	v_mul_f32_e32 v223, v215, v223
	v_fma_f32 v62, v62, s34, v220
	v_fma_f32 v63, v63, s34, v221
	v_fma_f32 v64, v64, s34, v222
	v_fma_f32 v65, v65, s34, v223
	s_waitcnt lgkmcnt(1)
	v_mul_f32_e32 v238, v212, v238
	v_mul_f32_e32 v239, v213, v239
	v_mul_f32_e32 v240, v214, v240
	v_mul_f32_e32 v241, v215, v241
	v_fma_f32 v66, v66, s34, v238
	v_fma_f32 v67, v67, s34, v239
	v_fma_f32 v68, v68, s34, v240
	v_fma_f32 v69, v69, s34, v241
	s_waitcnt lgkmcnt(0)
	v_mul_f32_e32 v242, v212, v242
	v_mul_f32_e32 v243, v213, v243
	v_mul_f32_e32 v244, v214, v244
	v_mul_f32_e32 v245, v215, v245
	v_fma_f32 v70, v70, s34, v242
	v_fma_f32 v71, v71, s34, v243
	v_fma_f32 v72, v72, s34, v244
	v_fma_f32 v73, v73, s34, v245
	global_store_dwordx4 v248, v[6:9], s[66:67] sc1
	s_add_u32 s66, s66, 0x4000
	s_addc_u32 s67, s67, 0
	global_store_dwordx4 v248, v[10:13], s[66:67] sc1
	s_add_u32 s66, s66, 0x4000
	s_addc_u32 s67, s67, 0
	global_store_dwordx4 v248, v[14:17], s[66:67] sc1
	s_add_u32 s66, s66, 0x4000
	s_addc_u32 s67, s67, 0
	global_store_dwordx4 v248, v[22:25], s[66:67] sc1
	s_add_u32 s66, s66, 0x4000
	s_addc_u32 s67, s67, 0
	global_store_dwordx4 v248, v[26:29], s[66:67] sc1
	s_add_u32 s66, s66, 0x4000
	s_addc_u32 s67, s67, 0
	global_store_dwordx4 v248, v[30:33], s[66:67] sc1
	s_add_u32 s66, s66, 0x4000
	s_addc_u32 s67, s67, 0
	global_store_dwordx4 v248, v[34:37], s[66:67] sc1
	s_add_u32 s66, s66, 0x4000
	s_addc_u32 s67, s67, 0
	global_store_dwordx4 v248, v[38:41], s[66:67] sc1
	s_add_u32 s66, s66, 0x4000
	s_addc_u32 s67, s67, 0
	global_store_dwordx4 v248, v[42:45], s[66:67] sc1
	s_add_u32 s66, s66, 0x4000
	s_addc_u32 s67, s67, 0
	global_store_dwordx4 v248, v[46:49], s[66:67] sc1
	s_add_u32 s66, s66, 0x4000
	s_addc_u32 s67, s67, 0
	global_store_dwordx4 v248, v[50:53], s[66:67] sc1
	s_add_u32 s66, s66, 0x4000
	s_addc_u32 s67, s67, 0
	global_store_dwordx4 v248, v[54:57], s[66:67] sc1
	s_add_u32 s66, s66, 0x4000
	s_addc_u32 s67, s67, 0
	global_store_dwordx4 v248, v[58:61], s[66:67] sc1
	s_add_u32 s66, s66, 0x4000
	s_addc_u32 s67, s67, 0
	global_store_dwordx4 v248, v[62:65], s[66:67] sc1
	s_add_u32 s66, s66, 0x4000
	s_addc_u32 s67, s67, 0
	global_store_dwordx4 v248, v[66:69], s[66:67] sc1
	s_add_u32 s66, s66, 0x4000
	s_addc_u32 s67, s67, 0
	global_store_dwordx4 v248, v[70:73], s[66:67] sc1
	s_add_u32 s66, s66, 0x4000
	s_addc_u32 s67, s67, 0
	v_mov_b32_e32 v236, 0x358637bd
	s_mov_b32 s60, s58
	s_mov_b32 s61, s59
	s_mov_b64 s[48:49], s[42:43]
	s_mov_b64 s[46:47], s[44:45]
	s_and_b64 vcc, exec, s[40:41]
	s_cbranch_vccz .LBB0_69
	s_branch .LBB0_73
